# up epilogue H stores with sc0 sc1 nt (policy sweep, on top of v70)
# baseline (speedup 1.0000x reference)
; __device__ __forceinline__ unsigned cvt_pk_bf16(float lo, float hi) { unsigned r; asm volatile("v_cvt_pk_bf16_f32 %0, %1, %2" : "=v"(r) : "v"(lo), "v"(hi)); return r; }
;     __device__ __forceinline__ void operator()(const f32x4 (&acc)[2][2][4][2], const Unit& u, int ui, int wr, int wc, int fr, int fq) const {
;     ...
;             for (int m = 0; m < 4; ++m) rs[ai][m] = row_rstd(lds, ui, ai * HALF + wr * 64 + m * 16 + fr);
; #pragma unroll
;         for (int ai = 0; ai < 2; ++ai)
; #pragma unroll
;             for (int m = 0; m < 4; ++m) { const float r = rs[ai][m]; const int row = row0 + ai * HALF + m * 16;
;                 const float c1 = r * -1.44269504089f, r2 = r * r; u32x4 w;
; #pragma unroll
;                 for (int n = 0; n < 2; ++n)
; #pragma unroll
;                     for (int p = 0; p < 2; ++p) { const f32x2 g = (f32x2){acc[ai][0][m][n][2 * p], acc[ai][0][m][n][2 * p + 1]}, uu = (f32x2){acc[ai][1][m][n][2 * p], acc[ai][1][m][n][2 * p + 1]};
;                         const f32x2 t = g * c1; f32x2 d; d.x = __builtin_amdgcn_exp2f(t.x); d.y = __builtin_amdgcn_exp2f(t.y); d = d + 1.0f;
;                         f32x2 q; q.x = __builtin_amdgcn_rcpf(d.x); q.y = __builtin_amdgcn_rcpf(d.y);
;                         const f32x2 hh = (g * uu) * (q * r2); w[2 * n + p] = cvt_pk_bf16(hh.x, hh.y); }
;                 __builtin_nontemporal_store(w, (u32x4*)(H + (size_t)row * ldh + col0)); }
.LBB0_449:
	v_mov_b32_e32 v140, v147
	v_mov_b32_e32 v167, v164
	v_pk_mul_f32 v[120:121], v[124:125], v[120:121]
	v_add_u32_e32 v171, s35, v140
	v_lshlrev_b32_e32 v140, 2, v171
	v_lshl_add_u32 v140, s48, 10, v140
	v_add_u32_e32 v140, 0x20400, v140
	ds_read2_b32 v[168:169], v140 offset1:16
	ds_read2_b32 v[162:163], v140 offset0:32 offset1:48
	ds_read2_b32 v[142:143], v140 offset0:128 offset1:144
	ds_read2_b32 v[140:141], v140 offset0:160 offset1:176
	v_pk_mul_f32 v[122:123], v[126:127], v[122:123]
	s_waitcnt lgkmcnt(0)
	v_mul_f32_e32 v172, 0xbfb8aa3b, v168
	v_pk_mul_f32 v[174:175], v[124:125], v[172:173] op_sel_hi:[1,0]
	v_pk_mul_f32 v[124:125], v[126:127], v[172:173] op_sel_hi:[1,0]
	v_exp_f32_e32 v174, v174
	v_exp_f32_e32 v175, v175
	v_exp_f32_e32 v124, v124
	v_exp_f32_e32 v125, v125
	v_mul_f32_e32 v168, v168, v168
	v_pk_add_f32 v[174:175], v[174:175], 1.0 op_sel_hi:[1,0]
	v_pk_mul_f32 v[112:113], v[116:117], v[112:113]
	v_rcp_f32_e32 v174, v174
	v_rcp_f32_e32 v175, v175
	v_pk_add_f32 v[124:125], v[124:125], 1.0 op_sel_hi:[1,0]
	v_pk_mul_f32 v[114:115], v[118:119], v[114:115]
	v_rcp_f32_e32 v124, v124
	v_rcp_f32_e32 v125, v125
	v_pk_mul_f32 v[126:127], v[168:169], v[174:175] op_sel_hi:[0,1]
	v_pk_mul_f32 v[120:121], v[120:121], v[126:127]
	v_pk_mul_f32 v[126:127], v[116:117], v[172:173] op_sel_hi:[1,0]
	v_pk_mul_f32 v[124:125], v[168:169], v[124:125] op_sel_hi:[0,1]
	v_exp_f32_e32 v126, v126
	v_exp_f32_e32 v127, v127
	v_pk_mul_f32 v[122:123], v[122:123], v[124:125]
	v_pk_mul_f32 v[124:125], v[118:119], v[172:173] op_sel_hi:[1,0]
	v_cvt_pk_bf16_f32 v120, v120, v121
	v_cvt_pk_bf16_f32 v121, v122, v123
	v_pk_add_f32 v[122:123], v[126:127], 1.0 op_sel_hi:[1,0]
	v_exp_f32_e32 v124, v124
	v_exp_f32_e32 v125, v125
	v_rcp_f32_e32 v122, v122
	v_rcp_f32_e32 v123, v123
	s_lshl_b32 s5, s47, 7
	v_pk_add_f32 v[116:117], v[124:125], 1.0 op_sel_hi:[1,0]
	s_or_b32 s5, s5, s36
	v_rcp_f32_e32 v116, v116
	v_rcp_f32_e32 v117, v117
	v_pk_mul_f32 v[118:119], v[168:169], v[122:123] op_sel_hi:[0,1]
	v_pk_mul_f32 v[112:113], v[112:113], v[118:119]
	v_mul_f32_e32 v118, 0xbfb8aa3b, v169
	v_cvt_pk_bf16_f32 v122, v112, v113
	v_pk_mul_f32 v[112:113], v[168:169], v[116:117] op_sel_hi:[0,1]
	v_pk_mul_f32 v[124:125], v[108:109], v[118:119] op_sel_hi:[1,0]
	v_lshl_add_u32 v170, v167, 3, s5
	v_pk_mul_f32 v[112:113], v[114:115], v[112:113]
	v_exp_f32_e32 v124, v124
	v_exp_f32_e32 v125, v125
	v_lshl_add_u32 v167, s46, 8, v171
	v_ashrrev_i32_e32 v171, 31, v170
	v_cvt_pk_bf16_f32 v123, v112, v113
	v_mov_b64_e32 v[112:113], s[20:21]
	v_pk_mul_f32 v[104:105], v[108:109], v[104:105]
	v_pk_mul_f32 v[108:109], v[110:111], v[118:119] op_sel_hi:[1,0]
	v_mad_i64_i32 v[116:117], s[14:15], v167, s59, v[112:113]
	v_lshlrev_b64 v[114:115], 1, v[170:171]
	v_exp_f32_e32 v108, v108
	v_exp_f32_e32 v109, v109
	v_lshl_add_u64 v[116:117], v[116:117], 0, v[114:115]
	global_store_dwordx4 v[116:117], v[120:123], off sc0 sc1 nt
	v_mul_f32_e32 v116, v169, v169
	v_pk_add_f32 v[108:109], v[108:109], 1.0 op_sel_hi:[1,0]
	v_pk_add_f32 v[120:121], v[124:125], 1.0 op_sel_hi:[1,0]
	v_rcp_f32_e32 v108, v108
	v_rcp_f32_e32 v120, v120
	v_rcp_f32_e32 v121, v121
	v_rcp_f32_e32 v109, v109
	v_pk_mul_f32 v[106:107], v[110:111], v[106:107]
	v_pk_mul_f32 v[96:97], v[100:101], v[96:97]
	v_pk_mul_f32 v[110:111], v[116:117], v[120:121] op_sel_hi:[0,1]
	v_pk_mul_f32 v[104:105], v[104:105], v[110:111]
	v_pk_mul_f32 v[110:111], v[100:101], v[118:119] op_sel_hi:[1,0]
	v_pk_mul_f32 v[108:109], v[116:117], v[108:109] op_sel_hi:[0,1]
	v_exp_f32_e32 v110, v110
	v_exp_f32_e32 v111, v111
	v_pk_mul_f32 v[106:107], v[106:107], v[108:109]
	v_pk_mul_f32 v[108:109], v[102:103], v[118:119] op_sel_hi:[1,0]
	v_cvt_pk_bf16_f32 v104, v104, v105
	v_cvt_pk_bf16_f32 v105, v106, v107
	v_pk_add_f32 v[106:107], v[110:111], 1.0 op_sel_hi:[1,0]
	v_exp_f32_e32 v108, v108
	v_exp_f32_e32 v109, v109
	v_rcp_f32_e32 v106, v106
	v_rcp_f32_e32 v107, v107
	v_pk_mul_f32 v[98:99], v[102:103], v[98:99]
	v_pk_add_f32 v[100:101], v[108:109], 1.0 op_sel_hi:[1,0]
	v_pk_mul_f32 v[88:89], v[92:93], v[88:89]
	v_rcp_f32_e32 v100, v100
	v_rcp_f32_e32 v101, v101
	v_pk_mul_f32 v[102:103], v[116:117], v[106:107] op_sel_hi:[0,1]
	v_pk_mul_f32 v[96:97], v[96:97], v[102:103]
	v_pk_mul_f32 v[90:91], v[94:95], v[90:91]
	v_cvt_pk_bf16_f32 v106, v96, v97
	v_pk_mul_f32 v[96:97], v[116:117], v[100:101] op_sel_hi:[0,1]
	v_pk_mul_f32 v[96:97], v[98:99], v[96:97]
	v_mul_f32_e32 v98, 0xbfb8aa3b, v162
	v_pk_mul_f32 v[100:101], v[92:93], v[98:99] op_sel_hi:[1,0]
	v_pk_mul_f32 v[92:93], v[94:95], v[98:99] op_sel_hi:[1,0]
	v_exp_f32_e32 v100, v100
	v_exp_f32_e32 v101, v101
	v_exp_f32_e32 v92, v92
	v_exp_f32_e32 v93, v93
	v_cvt_pk_bf16_f32 v107, v96, v97
	v_pk_add_f32 v[100:101], v[100:101], 1.0 op_sel_hi:[1,0]
	v_add_u32_e32 v96, 16, v167
	v_rcp_f32_e32 v100, v100
	v_rcp_f32_e32 v101, v101
	v_mad_i64_i32 v[96:97], s[14:15], v96, s59, v[112:113]
	v_pk_add_f32 v[92:93], v[92:93], 1.0 op_sel_hi:[1,0]
	v_lshl_add_u64 v[96:97], v[96:97], 0, v[114:115]
	v_rcp_f32_e32 v92, v92
	v_rcp_f32_e32 v93, v93
	global_store_dwordx4 v[96:97], v[104:107], off sc0 sc1 nt
	v_mul_f32_e32 v96, v162, v162
	v_pk_mul_f32 v[94:95], v[96:97], v[100:101] op_sel_hi:[0,1]
	v_pk_mul_f32 v[88:89], v[88:89], v[94:95]
	v_pk_mul_f32 v[94:95], v[84:85], v[98:99] op_sel_hi:[1,0]
	v_pk_mul_f32 v[92:93], v[96:97], v[92:93] op_sel_hi:[0,1]
	v_exp_f32_e32 v94, v94
	v_exp_f32_e32 v95, v95
	v_pk_mul_f32 v[90:91], v[90:91], v[92:93]
	v_pk_mul_f32 v[92:93], v[86:87], v[98:99] op_sel_hi:[1,0]
	v_cvt_pk_bf16_f32 v88, v88, v89
	v_cvt_pk_bf16_f32 v89, v90, v91
	v_pk_add_f32 v[90:91], v[94:95], 1.0 op_sel_hi:[1,0]
	v_exp_f32_e32 v92, v92
; __device__ __forceinline__ unsigned cvt_pk_bf16(float lo, float hi) { unsigned r; asm volatile("v_cvt_pk_bf16_f32 %0, %1, %2" : "=v"(r) : "v"(lo), "v"(hi)); return r; }
;     __device__ __forceinline__ void operator()(const f32x4 (&acc)[2][2][4][2], const Unit& u, int ui, int wr, int wc, int fr, int fq) const {
;     ...
;             for (int m = 0; m < 4; ++m) { const float r = rs[ai][m]; const int row = row0 + ai * HALF + m * 16;
;                 const float c1 = r * -1.44269504089f, r2 = r * r; u32x4 w;
; #pragma unroll
;                 for (int n = 0; n < 2; ++n)
; #pragma unroll
;                     for (int p = 0; p < 2; ++p) { const f32x2 g = (f32x2){acc[ai][0][m][n][2 * p], acc[ai][0][m][n][2 * p + 1]}, uu = (f32x2){acc[ai][1][m][n][2 * p], acc[ai][1][m][n][2 * p + 1]};
;                         const f32x2 t = g * c1; f32x2 d; d.x = __builtin_amdgcn_exp2f(t.x); d.y = __builtin_amdgcn_exp2f(t.y); d = d + 1.0f;
;                         f32x2 q; q.x = __builtin_amdgcn_rcpf(d.x); q.y = __builtin_amdgcn_rcpf(d.y);
;                         const f32x2 hh = (g * uu) * (q * r2); w[2 * n + p] = cvt_pk_bf16(hh.x, hh.y); }
;                 __builtin_nontemporal_store(w, (u32x4*)(H + (size_t)row * ldh + col0)); }
	v_exp_f32_e32 v93, v93
	v_rcp_f32_e32 v90, v90
	v_rcp_f32_e32 v91, v91
	v_pk_mul_f32 v[80:81], v[84:85], v[80:81]
	v_pk_add_f32 v[84:85], v[92:93], 1.0 op_sel_hi:[1,0]
	v_pk_mul_f32 v[82:83], v[86:87], v[82:83]
	v_rcp_f32_e32 v84, v84
	v_rcp_f32_e32 v85, v85
	v_pk_mul_f32 v[86:87], v[96:97], v[90:91] op_sel_hi:[0,1]
	v_pk_mul_f32 v[80:81], v[80:81], v[86:87]
	v_pk_mul_f32 v[72:73], v[76:77], v[72:73]
	v_cvt_pk_bf16_f32 v90, v80, v81
	v_pk_mul_f32 v[80:81], v[96:97], v[84:85] op_sel_hi:[0,1]
	v_pk_mul_f32 v[80:81], v[82:83], v[80:81]
	v_mul_f32_e32 v82, 0xbfb8aa3b, v163
	v_pk_mul_f32 v[84:85], v[76:77], v[82:83] op_sel_hi:[1,0]
	v_pk_mul_f32 v[76:77], v[78:79], v[82:83] op_sel_hi:[1,0]
	v_exp_f32_e32 v84, v84
	v_exp_f32_e32 v85, v85
	v_exp_f32_e32 v76, v76
	v_exp_f32_e32 v77, v77
	v_cvt_pk_bf16_f32 v91, v80, v81
	v_pk_add_f32 v[84:85], v[84:85], 1.0 op_sel_hi:[1,0]
	v_add_u32_e32 v80, 32, v167
	v_rcp_f32_e32 v84, v84
	v_rcp_f32_e32 v85, v85
	v_mad_i64_i32 v[80:81], s[14:15], v80, s59, v[112:113]
	v_pk_add_f32 v[76:77], v[76:77], 1.0 op_sel_hi:[1,0]
	v_lshl_add_u64 v[80:81], v[80:81], 0, v[114:115]
	v_rcp_f32_e32 v76, v76
	v_rcp_f32_e32 v77, v77
	global_store_dwordx4 v[80:81], v[88:91], off sc0 sc1 nt
	v_mul_f32_e32 v80, v163, v163
	v_pk_mul_f32 v[74:75], v[78:79], v[74:75]
	v_pk_mul_f32 v[78:79], v[80:81], v[84:85] op_sel_hi:[0,1]
	v_pk_mul_f32 v[72:73], v[72:73], v[78:79]
	v_pk_mul_f32 v[78:79], v[68:69], v[82:83] op_sel_hi:[1,0]
	v_pk_mul_f32 v[76:77], v[80:81], v[76:77] op_sel_hi:[0,1]
	v_exp_f32_e32 v78, v78
	v_exp_f32_e32 v79, v79
	v_pk_mul_f32 v[74:75], v[74:75], v[76:77]
	v_pk_mul_f32 v[76:77], v[70:71], v[82:83] op_sel_hi:[1,0]
	v_cvt_pk_bf16_f32 v72, v72, v73
	v_cvt_pk_bf16_f32 v73, v74, v75
	v_pk_add_f32 v[74:75], v[78:79], 1.0 op_sel_hi:[1,0]
	v_exp_f32_e32 v76, v76
	v_exp_f32_e32 v77, v77
	v_rcp_f32_e32 v74, v74
	v_rcp_f32_e32 v75, v75
	v_pk_mul_f32 v[64:65], v[68:69], v[64:65]
	v_pk_add_f32 v[68:69], v[76:77], 1.0 op_sel_hi:[1,0]
	v_pk_mul_f32 v[66:67], v[70:71], v[66:67]
	v_rcp_f32_e32 v68, v68
	v_rcp_f32_e32 v69, v69
	v_pk_mul_f32 v[70:71], v[80:81], v[74:75] op_sel_hi:[0,1]
	v_pk_mul_f32 v[64:65], v[64:65], v[70:71]
	v_pk_mul_f32 v[56:57], v[60:61], v[56:57]
	v_cvt_pk_bf16_f32 v74, v64, v65
	v_pk_mul_f32 v[64:65], v[80:81], v[68:69] op_sel_hi:[0,1]
	v_pk_mul_f32 v[64:65], v[66:67], v[64:65]
	v_mul_f32_e32 v66, 0xbfb8aa3b, v142
	v_pk_mul_f32 v[68:69], v[60:61], v[66:67] op_sel_hi:[1,0]
	v_pk_mul_f32 v[60:61], v[62:63], v[66:67] op_sel_hi:[1,0]
	v_exp_f32_e32 v68, v68
	v_exp_f32_e32 v69, v69
	v_exp_f32_e32 v60, v60
	v_exp_f32_e32 v61, v61
	v_cvt_pk_bf16_f32 v75, v64, v65
	v_pk_add_f32 v[68:69], v[68:69], 1.0 op_sel_hi:[1,0]
	v_add_u32_e32 v64, 48, v167
	v_rcp_f32_e32 v68, v68
	v_rcp_f32_e32 v69, v69
	v_mad_i64_i32 v[64:65], s[14:15], v64, s59, v[112:113]
	v_pk_add_f32 v[60:61], v[60:61], 1.0 op_sel_hi:[1,0]
	v_lshl_add_u64 v[64:65], v[64:65], 0, v[114:115]
	v_rcp_f32_e32 v60, v60
	v_rcp_f32_e32 v61, v61
	global_store_dwordx4 v[64:65], v[72:75], off sc0 sc1 nt
	v_add_u32_e32 v65, 0x80, v167
	v_mul_f32_e32 v64, v142, v142
	v_pk_mul_f32 v[58:59], v[62:63], v[58:59]
	v_pk_mul_f32 v[62:63], v[64:65], v[68:69] op_sel_hi:[0,1]
	v_pk_mul_f32 v[56:57], v[56:57], v[62:63]
	v_pk_mul_f32 v[62:63], v[52:53], v[66:67] op_sel_hi:[1,0]
	v_pk_mul_f32 v[60:61], v[64:65], v[60:61] op_sel_hi:[0,1]
	v_exp_f32_e32 v62, v62
	v_exp_f32_e32 v63, v63
	v_pk_mul_f32 v[58:59], v[58:59], v[60:61]
	v_pk_mul_f32 v[60:61], v[54:55], v[66:67] op_sel_hi:[1,0]
	v_cvt_pk_bf16_f32 v56, v56, v57
	v_cvt_pk_bf16_f32 v57, v58, v59
	v_pk_add_f32 v[58:59], v[62:63], 1.0 op_sel_hi:[1,0]
	v_exp_f32_e32 v60, v60
	v_exp_f32_e32 v61, v61
	v_rcp_f32_e32 v58, v58
	v_rcp_f32_e32 v59, v59
	v_pk_mul_f32 v[48:49], v[52:53], v[48:49]
	v_pk_add_f32 v[52:53], v[60:61], 1.0 op_sel_hi:[1,0]
	v_pk_mul_f32 v[50:51], v[54:55], v[50:51]
	v_rcp_f32_e32 v52, v52
	v_rcp_f32_e32 v53, v53
	v_pk_mul_f32 v[54:55], v[64:65], v[58:59] op_sel_hi:[0,1]
	v_pk_mul_f32 v[48:49], v[48:49], v[54:55]
	v_pk_mul_f32 v[40:41], v[44:45], v[40:41]
	v_cvt_pk_bf16_f32 v58, v48, v49
	v_pk_mul_f32 v[48:49], v[64:65], v[52:53] op_sel_hi:[0,1]
	v_pk_mul_f32 v[48:49], v[50:51], v[48:49]
	v_mul_f32_e32 v50, 0xbfb8aa3b, v143
	v_pk_mul_f32 v[52:53], v[44:45], v[50:51] op_sel_hi:[1,0]
	v_pk_mul_f32 v[44:45], v[46:47], v[50:51] op_sel_hi:[1,0]
	v_exp_f32_e32 v52, v52
	v_exp_f32_e32 v53, v53
	v_exp_f32_e32 v44, v44
	v_exp_f32_e32 v45, v45
	v_cvt_pk_bf16_f32 v59, v48, v49
	v_pk_add_f32 v[52:53], v[52:53], 1.0 op_sel_hi:[1,0]
	v_mad_i64_i32 v[48:49], s[14:15], v65, s59, v[112:113]
	v_rcp_f32_e32 v52, v52
	v_rcp_f32_e32 v53, v53
	v_pk_add_f32 v[44:45], v[44:45], 1.0 op_sel_hi:[1,0]
	v_lshl_add_u64 v[48:49], v[48:49], 0, v[114:115]
	v_rcp_f32_e32 v44, v44
	v_rcp_f32_e32 v45, v45
	global_store_dwordx4 v[48:49], v[56:59], off sc0 sc1 nt
	v_mul_f32_e32 v48, v143, v143
	v_pk_mul_f32 v[42:43], v[46:47], v[42:43]
; __device__ __forceinline__ unsigned cvt_pk_bf16(float lo, float hi) { unsigned r; asm volatile("v_cvt_pk_bf16_f32 %0, %1, %2" : "=v"(r) : "v"(lo), "v"(hi)); return r; }
;     __device__ __forceinline__ void operator()(const f32x4 (&acc)[2][2][4][2], const Unit& u, int ui, int wr, int wc, int fr, int fq) const {
;     ...
;             for (int m = 0; m < 4; ++m) { const float r = rs[ai][m]; const int row = row0 + ai * HALF + m * 16;
;                 const float c1 = r * -1.44269504089f, r2 = r * r; u32x4 w;
; #pragma unroll
;                 for (int n = 0; n < 2; ++n)
; #pragma unroll
;                     for (int p = 0; p < 2; ++p) { const f32x2 g = (f32x2){acc[ai][0][m][n][2 * p], acc[ai][0][m][n][2 * p + 1]}, uu = (f32x2){acc[ai][1][m][n][2 * p], acc[ai][1][m][n][2 * p + 1]};
;                         const f32x2 t = g * c1; f32x2 d; d.x = __builtin_amdgcn_exp2f(t.x); d.y = __builtin_amdgcn_exp2f(t.y); d = d + 1.0f;
;                         f32x2 q; q.x = __builtin_amdgcn_rcpf(d.x); q.y = __builtin_amdgcn_rcpf(d.y);
;                         const f32x2 hh = (g * uu) * (q * r2); w[2 * n + p] = cvt_pk_bf16(hh.x, hh.y); }
;                 __builtin_nontemporal_store(w, (u32x4*)(H + (size_t)row * ldh + col0)); }
	v_pk_mul_f32 v[46:47], v[48:49], v[52:53] op_sel_hi:[0,1]
	v_pk_mul_f32 v[40:41], v[40:41], v[46:47]
	v_pk_mul_f32 v[46:47], v[36:37], v[50:51] op_sel_hi:[1,0]
	v_pk_mul_f32 v[44:45], v[48:49], v[44:45] op_sel_hi:[0,1]
	v_exp_f32_e32 v46, v46
	v_exp_f32_e32 v47, v47
	v_pk_mul_f32 v[42:43], v[42:43], v[44:45]
	v_pk_mul_f32 v[44:45], v[38:39], v[50:51] op_sel_hi:[1,0]
	v_cvt_pk_bf16_f32 v40, v40, v41
	v_cvt_pk_bf16_f32 v41, v42, v43
	v_pk_add_f32 v[42:43], v[46:47], 1.0 op_sel_hi:[1,0]
	v_exp_f32_e32 v44, v44
	v_exp_f32_e32 v45, v45
	v_rcp_f32_e32 v42, v42
	v_rcp_f32_e32 v43, v43
	v_pk_mul_f32 v[32:33], v[36:37], v[32:33]
	v_pk_add_f32 v[36:37], v[44:45], 1.0 op_sel_hi:[1,0]
	v_pk_mul_f32 v[34:35], v[38:39], v[34:35]
	v_rcp_f32_e32 v36, v36
	v_rcp_f32_e32 v37, v37
	v_pk_mul_f32 v[38:39], v[48:49], v[42:43] op_sel_hi:[0,1]
	v_pk_mul_f32 v[32:33], v[32:33], v[38:39]
	v_pk_mul_f32 v[24:25], v[28:29], v[24:25]
	v_cvt_pk_bf16_f32 v42, v32, v33
	v_pk_mul_f32 v[32:33], v[48:49], v[36:37] op_sel_hi:[0,1]
	v_pk_mul_f32 v[32:33], v[34:35], v[32:33]
	v_mul_f32_e32 v34, 0xbfb8aa3b, v140
	v_pk_mul_f32 v[36:37], v[28:29], v[34:35] op_sel_hi:[1,0]
	v_pk_mul_f32 v[28:29], v[30:31], v[34:35] op_sel_hi:[1,0]
	v_exp_f32_e32 v36, v36
	v_exp_f32_e32 v37, v37
	v_exp_f32_e32 v28, v28
	v_exp_f32_e32 v29, v29
	v_cvt_pk_bf16_f32 v43, v32, v33
	v_pk_add_f32 v[36:37], v[36:37], 1.0 op_sel_hi:[1,0]
	v_add_u32_e32 v32, 0x90, v167
	v_rcp_f32_e32 v36, v36
	v_rcp_f32_e32 v37, v37
	v_mad_i64_i32 v[32:33], s[14:15], v32, s59, v[112:113]
	v_pk_add_f32 v[28:29], v[28:29], 1.0 op_sel_hi:[1,0]
	v_lshl_add_u64 v[32:33], v[32:33], 0, v[114:115]
	v_rcp_f32_e32 v28, v28
	v_rcp_f32_e32 v29, v29
	global_store_dwordx4 v[32:33], v[40:43], off sc0 sc1 nt
	v_mul_f32_e32 v32, v140, v140
	v_pk_mul_f32 v[26:27], v[30:31], v[26:27]
	v_pk_mul_f32 v[30:31], v[32:33], v[36:37] op_sel_hi:[0,1]
	v_pk_mul_f32 v[24:25], v[24:25], v[30:31]
	v_pk_mul_f32 v[30:31], v[20:21], v[34:35] op_sel_hi:[1,0]
	v_pk_mul_f32 v[28:29], v[32:33], v[28:29] op_sel_hi:[0,1]
	v_exp_f32_e32 v30, v30
	v_exp_f32_e32 v31, v31
	v_pk_mul_f32 v[26:27], v[26:27], v[28:29]
	v_pk_mul_f32 v[28:29], v[22:23], v[34:35] op_sel_hi:[1,0]
	v_cvt_pk_bf16_f32 v24, v24, v25
	v_cvt_pk_bf16_f32 v25, v26, v27
	v_pk_add_f32 v[26:27], v[30:31], 1.0 op_sel_hi:[1,0]
	v_exp_f32_e32 v28, v28
	v_exp_f32_e32 v29, v29
	v_rcp_f32_e32 v26, v26
	v_rcp_f32_e32 v27, v27
	v_pk_mul_f32 v[16:17], v[20:21], v[16:17]
	v_pk_add_f32 v[20:21], v[28:29], 1.0 op_sel_hi:[1,0]
	v_pk_mul_f32 v[18:19], v[22:23], v[18:19]
	v_rcp_f32_e32 v20, v20
	v_rcp_f32_e32 v21, v21
	v_pk_mul_f32 v[22:23], v[32:33], v[26:27] op_sel_hi:[0,1]
	v_pk_mul_f32 v[16:17], v[16:17], v[22:23]
	v_pk_mul_f32 v[8:9], v[12:13], v[8:9]
	v_cvt_pk_bf16_f32 v26, v16, v17
	v_pk_mul_f32 v[16:17], v[32:33], v[20:21] op_sel_hi:[0,1]
	v_pk_mul_f32 v[16:17], v[18:19], v[16:17]
	v_mul_f32_e32 v18, 0xbfb8aa3b, v141
	v_pk_mul_f32 v[20:21], v[12:13], v[18:19] op_sel_hi:[1,0]
	v_pk_mul_f32 v[12:13], v[14:15], v[18:19] op_sel_hi:[1,0]
	v_exp_f32_e32 v20, v20
	v_exp_f32_e32 v21, v21
	v_exp_f32_e32 v12, v12
	v_exp_f32_e32 v13, v13
	v_cvt_pk_bf16_f32 v27, v16, v17
	v_pk_add_f32 v[20:21], v[20:21], 1.0 op_sel_hi:[1,0]
	v_add_u32_e32 v16, 0xa0, v167
	v_rcp_f32_e32 v20, v20
	v_rcp_f32_e32 v21, v21
	v_mad_i64_i32 v[16:17], s[14:15], v16, s59, v[112:113]
	v_pk_add_f32 v[12:13], v[12:13], 1.0 op_sel_hi:[1,0]
	v_lshl_add_u64 v[16:17], v[16:17], 0, v[114:115]
	v_rcp_f32_e32 v12, v12
	v_rcp_f32_e32 v13, v13
	global_store_dwordx4 v[16:17], v[24:27], off sc0 sc1 nt
	v_mul_f32_e32 v16, v141, v141
	v_pk_mul_f32 v[10:11], v[14:15], v[10:11]
	v_pk_mul_f32 v[14:15], v[16:17], v[20:21] op_sel_hi:[0,1]
	v_pk_mul_f32 v[8:9], v[8:9], v[14:15]
	v_pk_mul_f32 v[14:15], v[4:5], v[18:19] op_sel_hi:[1,0]
	v_pk_mul_f32 v[12:13], v[16:17], v[12:13] op_sel_hi:[0,1]
	v_exp_f32_e32 v14, v14
	v_exp_f32_e32 v15, v15
	v_pk_mul_f32 v[10:11], v[10:11], v[12:13]
	v_pk_mul_f32 v[12:13], v[6:7], v[18:19] op_sel_hi:[1,0]
	v_cvt_pk_bf16_f32 v8, v8, v9
	v_cvt_pk_bf16_f32 v9, v10, v11
	v_pk_add_f32 v[10:11], v[14:15], 1.0 op_sel_hi:[1,0]
	v_exp_f32_e32 v12, v12
	v_exp_f32_e32 v13, v13
	v_rcp_f32_e32 v10, v10
	v_rcp_f32_e32 v11, v11
	v_pk_mul_f32 v[0:1], v[4:5], v[0:1]
	v_pk_add_f32 v[4:5], v[12:13], 1.0 op_sel_hi:[1,0]
	v_pk_mul_f32 v[2:3], v[6:7], v[2:3]
	v_rcp_f32_e32 v4, v4
	v_rcp_f32_e32 v5, v5
	v_pk_mul_f32 v[6:7], v[16:17], v[10:11] op_sel_hi:[0,1]
	v_pk_mul_f32 v[0:1], v[0:1], v[6:7]
	s_andn2_b64 vcc, exec, s[8:9]
	v_cvt_pk_bf16_f32 v10, v0, v1
	v_pk_mul_f32 v[0:1], v[16:17], v[4:5] op_sel_hi:[0,1]
	v_pk_mul_f32 v[0:1], v[2:3], v[0:1]
	s_mov_b64 s[8:9], -1
	v_cvt_pk_bf16_f32 v11, v0, v1
	v_add_u32_e32 v0, 0xb0, v167
	v_mad_i64_i32 v[0:1], s[14:15], v0, s59, v[112:113]
	v_lshl_add_u64 v[0:1], v[0:1], 0, v[114:115]
	global_store_dwordx4 v[0:1], v[8:11], off sc0 sc1 nt
	s_cbranch_vccnz .LBB0_442
	s_andn2_b64 vcc, exec, s[0:1]
	s_cbranch_vccnz .LBB0_441
	s_barrier
	s_branch .LBB0_441
